# diff-attention unit epilogue: sub-LN gain loads prefetched three ahead, the 16 output stores issued together at the end (no wait on store completion per chunk)
# speedup vs baseline: 1.0520x; 1.0024x over previous
; DI unsigned pk_bf16(float a, float b) { f32x2 v = {a, b}; return __builtin_bit_cast(unsigned, __builtin_convertvector(v, bf16v2)); }
; DI float bflo(unsigned u) { return __uint_as_float(u << 16); }
; DI float bfhi(unsigned u) { return __uint_as_float(u & 0xffff0000u); }
; DI float xhalf_sum(float x) { auto rr = __builtin_amdgcn_permlane32_swap(__float_as_uint(x), __float_as_uint(x), false, false); return __uint_as_float(rr[0]) + __uint_as_float(rr[1]); }
;     ...
;         const float l = xhalf_sum(hsum16(lv));
;         if (probe) {
;             float chk = l + m;
; #pragma unroll
;             for (int dt = 0; dt < 4; ++dt)
; #pragma unroll
;                 for (int i = 0; i < 16; ++i) chk += o[dt][i];
;             if (chk == 1.2345e-30f) ((float*)(p.ws + OFF_CTL))[32] = chk;
;             continue;
;         }
;         const float inv = 1.f / l;
;         bf16_t* O = (bf16_t*)(p.ws + OFF_O) + ((size_t)b * 4096 + qpos) * 1024 + hh * 128;
;         if (mp == 0) {
; #pragma unroll
;             for (int dt = 0; dt < 4; ++dt)
; #pragma unroll
;                 for (int g4 = 0; g4 < 4; ++g4) {
;                     u32x2 ov; ov.x = pk_bf16(o[dt][4 * g4] * inv, o[dt][4 * g4 + 1] * inv); ov.y = pk_bf16(o[dt][4 * g4 + 2] * inv, o[dt][4 * g4 + 3] * inv);
;                     *(u32x2*)(O + dt * 32 + 8 * g4 + 4 * h) = ov;
;                 }
;         } else {
;             float ss = 0.f;
;             const float li = lam * inv;
; #pragma unroll
;             for (int dt = 0; dt < 4; ++dt)
; #pragma unroll
;                 for (int g4 = 0; g4 < 4; ++g4) {
;                     const u32x2 pv = *(const u32x2*)(O + dt * 32 + 8 * g4 + 4 * h);
;                     const float v0 = bflo(pv.x) - li * o[dt][4 * g4], v1 = bfhi(pv.x) - li * o[dt][4 * g4 + 1];
;                     const float v2 = bflo(pv.y) - li * o[dt][4 * g4 + 2], v3 = bfhi(pv.y) - li * o[dt][4 * g4 + 3];
;                     o[dt][4 * g4] = v0; o[dt][4 * g4 + 1] = v1; o[dt][4 * g4 + 2] = v2; o[dt][4 * g4 + 3] = v3;
;                     ss += (v0 * v0 + v1 * v1) + (v2 * v2 + v3 * v3);
;                 }
;             ss = xhalf_sum(ss);
.LBB0_479:
	s_or_b64 exec, exec, s[2:3]
	v_pk_add_f32 v[4:5], v[86:87], v[94:95]
	v_pk_add_f32 v[6:7], v[88:89], v[96:97]
	v_pk_add_f32 v[8:9], v[84:85], v[92:93]
	v_pk_add_f32 v[10:11], v[82:83], v[90:91]
	v_pk_add_f32 v[6:7], v[8:9], v[6:7]
	v_pk_add_f32 v[4:5], v[10:11], v[4:5]
	s_nop 0
	v_add_f32_e32 v2, v4, v5
	v_add_f32_e32 v4, v6, v7
	v_add_f32_e32 v2, v2, v4
	v_mov_b32_e32 v4, v2
	s_nop 1
	v_permlane32_swap_b32_e32 v2, v4
	v_add_f32_e32 v2, v2, v4
	v_div_scale_f32 v4, s[2:3], v2, v2, 1.0
	v_rcp_f32_e32 v5, v4
	s_mov_b64 s[2:3], -1
	v_fma_f32 v6, -v4, v5, 1.0
	v_fmac_f32_e32 v5, v6, v5
	v_div_scale_f32 v6, vcc, 1.0, v2, 1.0
	v_mul_f32_e32 v7, v6, v5
	v_fma_f32 v8, -v4, v7, v6
	v_fmac_f32_e32 v7, v8, v5
	v_fma_f32 v4, -v4, v7, v6
	v_div_fmas_f32 v4, v4, v5, v7
	v_div_fixup_f32 v2, v4, v2, 1.0
	s_and_b64 vcc, exec, s[20:21]
	s_cbranch_vccz .LBB0_481
	global_load_dwordx2 v[14:15], v[176:177], off
	global_load_dwordx2 v[82:83], v[176:177], off offset:16
	global_load_dwordx2 v[84:85], v[176:177], off offset:32
	global_load_dwordx2 v[86:87], v[176:177], off offset:48
	global_load_dwordx2 v[90:91], v[176:177], off offset:64
	global_load_dwordx2 v[92:93], v[176:177], off offset:80
	global_load_dwordx2 v[104:105], v[176:177], off offset:96
	global_load_dwordx2 v[114:115], v[176:177], off offset:112
	global_load_dwordx2 v[118:119], v[176:177], off offset:128
	global_load_dwordx2 v[124:125], v[176:177], off offset:144
	global_load_dwordx2 v[120:121], v[176:177], off offset:160
	global_load_dwordx2 v[98:99], v[176:177], off offset:176
	global_load_dwordx2 v[88:89], v[176:177], off offset:192
	global_load_dwordx2 v[16:17], v[176:177], off offset:208
	global_load_dwordx2 v[12:13], v[176:177], off offset:224
	global_load_dwordx2 v[10:11], v[176:177], off offset:240
	global_load_dwordx4 v[4:7], v[178:179], off
	v_mul_f32_e32 v8, v185, v2
	s_waitcnt vmcnt(16)
	v_lshlrev_b32_e32 v94, 16, v15
	v_and_b32_e32 v95, 0xffff0000, v15
	v_lshlrev_b32_e32 v96, 16, v14
	v_and_b32_e32 v97, 0xffff0000, v14
	s_waitcnt vmcnt(15)
	v_lshlrev_b32_e32 v14, 16, v83
	v_and_b32_e32 v15, 0xffff0000, v83
	v_lshlrev_b32_e32 v100, 16, v82
	v_and_b32_e32 v101, 0xffff0000, v82
	s_waitcnt vmcnt(13)
	v_lshlrev_b32_e32 v116, 16, v86
	v_and_b32_e32 v117, 0xffff0000, v86
	v_pk_fma_f32 v[108:109], v[68:69], v[8:9], v[94:95] op_sel_hi:[1,0,1] neg_lo:[1,0,0] neg_hi:[1,0,0]
	v_pk_fma_f32 v[112:113], v[66:67], v[8:9], v[96:97] op_sel_hi:[1,0,1] neg_lo:[1,0,0] neg_hi:[1,0,0]
	v_pk_fma_f32 v[102:103], v[72:73], v[8:9], v[14:15] op_sel_hi:[1,0,1] neg_lo:[1,0,0] neg_hi:[1,0,0]
	v_pk_fma_f32 v[106:107], v[70:71], v[8:9], v[100:101] op_sel_hi:[1,0,1] neg_lo:[1,0,0] neg_hi:[1,0,0]
	v_lshlrev_b32_e32 v82, 16, v85
	v_and_b32_e32 v83, 0xffff0000, v85
	v_lshlrev_b32_e32 v110, 16, v84
	v_and_b32_e32 v111, 0xffff0000, v84
	s_waitcnt vmcnt(12)
	v_lshlrev_b32_e32 v122, 16, v91
	v_and_b32_e32 v123, 0xffff0000, v91
	v_lshlrev_b32_e32 v126, 16, v90
	v_and_b32_e32 v127, 0xffff0000, v90
	v_pk_fma_f32 v[90:91], v[78:79], v[8:9], v[116:117] op_sel_hi:[1,0,1] neg_lo:[1,0,0] neg_hi:[1,0,0]
	v_mov_b32_e32 v100, v113
	v_mov_b32_e32 v101, v109
	v_mov_b32_e32 v116, v107
	v_mov_b32_e32 v117, v103
	v_lshlrev_b32_e32 v84, 16, v87
	v_and_b32_e32 v85, 0xffff0000, v87
	s_waitcnt vmcnt(11)
	v_lshlrev_b32_e32 v128, 16, v93
	v_and_b32_e32 v129, 0xffff0000, v93
	v_lshlrev_b32_e32 v130, 16, v92
	v_and_b32_e32 v131, 0xffff0000, v92
	v_pk_fma_f32 v[92:93], v[76:77], v[8:9], v[82:83] op_sel_hi:[1,0,1] neg_lo:[1,0,0] neg_hi:[1,0,0]
	v_pk_fma_f32 v[96:97], v[74:75], v[8:9], v[110:111] op_sel_hi:[1,0,1] neg_lo:[1,0,0] neg_hi:[1,0,0]
	v_mov_b32_e32 v94, v112
	v_mov_b32_e32 v95, v108
	v_mov_b32_e32 v110, v106
	v_mov_b32_e32 v111, v102
	v_pk_mul_f32 v[100:101], v[100:101], v[100:101]
	v_pk_mul_f32 v[116:117], v[116:117], v[116:117]
	v_pk_fma_f32 v[86:87], v[80:81], v[8:9], v[84:85] op_sel_hi:[1,0,1] neg_lo:[1,0,0] neg_hi:[1,0,0]
	v_pk_fma_f32 v[82:83], v[52:53], v[8:9], v[122:123] op_sel_hi:[1,0,1] neg_lo:[1,0,0] neg_hi:[1,0,0]
	v_pk_fma_f32 v[84:85], v[50:51], v[8:9], v[126:127] op_sel_hi:[1,0,1] neg_lo:[1,0,0] neg_hi:[1,0,0]
	v_mul_f32_e32 v122, v93, v93
	v_mul_f32_e32 v126, v97, v97
	v_pk_fma_f32 v[94:95], v[94:95], v[94:95], v[100:101]
	v_pk_fma_f32 v[100:101], v[110:111], v[110:111], v[116:117]
	v_pk_fma_f32 v[14:15], v[56:57], v[8:9], v[128:129] op_sel_hi:[1,0,1] neg_lo:[1,0,0] neg_hi:[1,0,0]
	v_pk_mul_f32 v[128:129], v[86:87], v[86:87]
	v_pk_mul_f32 v[132:133], v[90:91], v[90:91]
	v_pk_fma_f32 v[122:123], v[92:93], v[92:93], v[122:123] op_sel_hi:[1,1,0]
	v_pk_fma_f32 v[126:127], v[96:97], v[96:97], v[126:127] op_sel_hi:[1,1,0]
	v_pk_add_f32 v[94:95], v[94:95], v[94:95] op_sel:[0,1] op_sel_hi:[1,0]
	v_pk_add_f32 v[100:101], v[100:101], v[100:101] op_sel:[0,1] op_sel_hi:[1,0]
	v_mov_b32_e32 v127, v128
	v_mov_b32_e32 v123, v129
	v_mov_b32_e32 v95, v132
	v_mov_b32_e32 v101, v133
	v_pk_add_f32 v[116:117], v[126:127], v[122:123]
	v_pk_add_f32 v[94:95], v[94:95], v[100:101]
	v_pk_fma_f32 v[100:101], v[54:55], v[8:9], v[130:131] op_sel_hi:[1,0,1] neg_lo:[1,0,0] neg_hi:[1,0,0]
	v_pk_add_f32 v[94:95], v[94:95], v[116:117]
	v_mov_b32_e32 v136, v85
	v_mov_b32_e32 v137, v83
	v_pk_add_f32 v[116:117], v[94:95], v[94:95] op_sel:[0,1] op_sel_hi:[1,0]
	v_mul_f32_e32 v94, v101, v101
	v_mov_b32_e32 v134, v84
	v_mov_b32_e32 v135, v82
	v_pk_mul_f32 v[136:137], v[136:137], v[136:137]
	v_pk_fma_f32 v[122:123], v[100:101], v[100:101], v[94:95] op_sel_hi:[1,1,0]
	s_waitcnt vmcnt(10)
; DI float bflo(unsigned u) { return __uint_as_float(u << 16); }
; DI float bfhi(unsigned u) { return __uint_as_float(u & 0xffff0000u); }
;     ...
;             float ss = 0.f;
;             const float li = lam * inv;
; #pragma unroll
;             for (int dt = 0; dt < 4; ++dt)
; #pragma unroll
;                 for (int g4 = 0; g4 < 4; ++g4) {
;                     const u32x2 pv = *(const u32x2*)(O + dt * 32 + 8 * g4 + 4 * h);
;                     const float v0 = bflo(pv.x) - li * o[dt][4 * g4], v1 = bfhi(pv.x) - li * o[dt][4 * g4 + 1];
;                     const float v2 = bflo(pv.y) - li * o[dt][4 * g4 + 2], v3 = bfhi(pv.y) - li * o[dt][4 * g4 + 3];
;                     o[dt][4 * g4] = v0; o[dt][4 * g4 + 1] = v1; o[dt][4 * g4 + 2] = v2; o[dt][4 * g4 + 3] = v3;
;                     ss += (v0 * v0 + v1 * v1) + (v2 * v2 + v3 * v3);
;                 }
	v_lshlrev_b32_e32 v94, 16, v105
	v_and_b32_e32 v95, 0xffff0000, v105
	v_lshlrev_b32_e32 v128, 16, v104
	v_and_b32_e32 v129, 0xffff0000, v104
	v_mul_f32_e32 v138, v15, v15
	v_pk_fma_f32 v[110:111], v[134:135], v[134:135], v[136:137]
	v_pk_fma_f32 v[94:95], v[60:61], v[8:9], v[94:95] op_sel_hi:[1,0,1] neg_lo:[1,0,0] neg_hi:[1,0,0]
	v_pk_fma_f32 v[104:105], v[58:59], v[8:9], v[128:129] op_sel_hi:[1,0,1] neg_lo:[1,0,0] neg_hi:[1,0,0]
	v_pk_fma_f32 v[138:139], v[14:15], v[14:15], v[138:139] op_sel_hi:[1,1,0]
	v_pk_add_f32 v[110:111], v[110:111], v[110:111] op_sel:[0,1] op_sel_hi:[1,0]
	v_pk_mul_f32 v[126:127], v[94:95], v[94:95]
	v_pk_mul_f32 v[128:129], v[104:105], v[104:105]
	v_mov_b32_e32 v123, v126
	v_mov_b32_e32 v139, v127
	v_mov_b32_e32 v117, v128
	v_mov_b32_e32 v111, v129
	v_pk_add_f32 v[122:123], v[122:123], v[138:139]
	v_pk_add_f32 v[110:111], v[116:117], v[110:111]
	s_waitcnt vmcnt(9)
	v_lshlrev_b32_e32 v116, 16, v114
	v_pk_add_f32 v[110:111], v[110:111], v[122:123]
	v_and_b32_e32 v117, 0xffff0000, v114
	v_pk_add_f32 v[126:127], v[110:111], v[110:111] op_sel:[0,1] op_sel_hi:[1,0]
	v_lshlrev_b32_e32 v110, 16, v115
	v_and_b32_e32 v111, 0xffff0000, v115
	v_pk_fma_f32 v[110:111], v[64:65], v[8:9], v[110:111] op_sel_hi:[1,0,1] neg_lo:[1,0,0] neg_hi:[1,0,0]
	v_pk_fma_f32 v[116:117], v[62:63], v[8:9], v[116:117] op_sel_hi:[1,0,1] neg_lo:[1,0,0] neg_hi:[1,0,0]
	v_mov_b32_e32 v123, v111
	v_mov_b32_e32 v122, v117
	v_mov_b32_e32 v114, v116
	v_mov_b32_e32 v115, v110
	v_pk_mul_f32 v[122:123], v[122:123], v[122:123]
	s_waitcnt vmcnt(7)
	v_lshlrev_b32_e32 v136, 16, v124
	v_pk_fma_f32 v[114:115], v[114:115], v[114:115], v[122:123]
	v_and_b32_e32 v137, 0xffff0000, v124
	v_pk_add_f32 v[128:129], v[114:115], v[114:115] op_sel:[0,1] op_sel_hi:[1,0]
	v_lshlrev_b32_e32 v114, 16, v119
	v_and_b32_e32 v115, 0xffff0000, v119
	v_pk_fma_f32 v[114:115], v[36:37], v[8:9], v[114:115] op_sel_hi:[1,0,1] neg_lo:[1,0,0] neg_hi:[1,0,0]
	s_waitcnt vmcnt(4)
	v_lshlrev_b32_e32 v142, 16, v88
	v_mul_f32_e32 v122, v115, v115
	v_pk_fma_f32 v[130:131], v[114:115], v[114:115], v[122:123] op_sel_hi:[1,1,0]
	v_lshlrev_b32_e32 v122, 16, v118
	v_and_b32_e32 v123, 0xffff0000, v118
	v_pk_fma_f32 v[122:123], v[34:35], v[8:9], v[122:123] op_sel_hi:[1,0,1] neg_lo:[1,0,0] neg_hi:[1,0,0]
	v_and_b32_e32 v143, 0xffff0000, v88
	v_mul_f32_e32 v118, v123, v123
	v_pk_fma_f32 v[132:133], v[122:123], v[122:123], v[118:119] op_sel_hi:[1,1,0]
	v_lshlrev_b32_e32 v118, 16, v125
	v_and_b32_e32 v119, 0xffff0000, v125
	v_pk_fma_f32 v[118:119], v[40:41], v[8:9], v[118:119] op_sel_hi:[1,0,1] neg_lo:[1,0,0] neg_hi:[1,0,0]
	v_pk_fma_f32 v[124:125], v[38:39], v[8:9], v[136:137] op_sel_hi:[1,0,1] neg_lo:[1,0,0] neg_hi:[1,0,0]
	v_pk_mul_f32 v[134:135], v[118:119], v[118:119]
	v_pk_mul_f32 v[136:137], v[124:125], v[124:125]
	v_mov_b32_e32 v133, v134
	v_mov_b32_e32 v131, v135
	v_mov_b32_e32 v127, v136
	v_mov_b32_e32 v129, v137
	v_pk_add_f32 v[130:131], v[132:133], v[130:131]
	v_pk_add_f32 v[126:127], v[126:127], v[128:129]
	v_lshlrev_b32_e32 v128, 16, v120
	v_pk_add_f32 v[126:127], v[126:127], v[130:131]
	v_and_b32_e32 v129, 0xffff0000, v120
	v_pk_add_f32 v[132:133], v[126:127], v[126:127] op_sel:[0,1] op_sel_hi:[1,0]
	v_lshlrev_b32_e32 v126, 16, v121
	v_and_b32_e32 v127, 0xffff0000, v121
	v_pk_fma_f32 v[126:127], v[44:45], v[8:9], v[126:127] op_sel_hi:[1,0,1] neg_lo:[1,0,0] neg_hi:[1,0,0]
	v_pk_fma_f32 v[128:129], v[42:43], v[8:9], v[128:129] op_sel_hi:[1,0,1] neg_lo:[1,0,0] neg_hi:[1,0,0]
	v_mov_b32_e32 v131, v127
	v_mov_b32_e32 v130, v129
	v_mov_b32_e32 v120, v128
	v_mov_b32_e32 v121, v126
	v_pk_mul_f32 v[130:131], v[130:131], v[130:131]
	s_waitcnt vmcnt(1)
	v_lshlrev_b32_e32 v144, 16, v11
	v_pk_fma_f32 v[120:121], v[120:121], v[120:121], v[130:131]
	v_and_b32_e32 v145, 0xffff0000, v11
	v_pk_add_f32 v[134:135], v[120:121], v[120:121] op_sel:[0,1] op_sel_hi:[1,0]
	v_lshlrev_b32_e32 v120, 16, v99
	v_and_b32_e32 v121, 0xffff0000, v99
	v_pk_fma_f32 v[120:121], v[48:49], v[8:9], v[120:121] op_sel_hi:[1,0,1] neg_lo:[1,0,0] neg_hi:[1,0,0]
	v_lshlrev_b32_e32 v148, 16, v10
	v_mul_f32_e32 v130, v121, v121
	v_pk_fma_f32 v[136:137], v[120:121], v[120:121], v[130:131] op_sel_hi:[1,1,0]
	v_lshlrev_b32_e32 v130, 16, v98
	v_and_b32_e32 v131, 0xffff0000, v98
	v_pk_fma_f32 v[130:131], v[46:47], v[8:9], v[130:131] op_sel_hi:[1,0,1] neg_lo:[1,0,0] neg_hi:[1,0,0]
	v_and_b32_e32 v149, 0xffff0000, v10
	v_mul_f32_e32 v98, v131, v131
	v_pk_fma_f32 v[138:139], v[130:131], v[130:131], v[98:99] op_sel_hi:[1,1,0]
	v_lshlrev_b32_e32 v98, 16, v89
	v_and_b32_e32 v99, 0xffff0000, v89
	v_pk_fma_f32 v[98:99], v[20:21], v[8:9], v[98:99] op_sel_hi:[1,0,1] neg_lo:[1,0,0] neg_hi:[1,0,0]
	v_pk_fma_f32 v[88:89], v[18:19], v[8:9], v[142:143] op_sel_hi:[1,0,1] neg_lo:[1,0,0] neg_hi:[1,0,0]
	v_pk_mul_f32 v[140:141], v[98:99], v[98:99]
	v_pk_mul_f32 v[142:143], v[88:89], v[88:89]
	v_mov_b32_e32 v139, v140
	v_mov_b32_e32 v137, v141
	v_mov_b32_e32 v133, v142
	v_mov_b32_e32 v135, v143
	v_pk_add_f32 v[136:137], v[138:139], v[136:137]
	v_pk_add_f32 v[132:133], v[132:133], v[134:135]
	v_lshlrev_b32_e32 v142, 16, v12
	v_pk_add_f32 v[132:133], v[132:133], v[136:137]
	v_lshlrev_b32_e32 v136, 16, v16
	v_pk_add_f32 v[134:135], v[132:133], v[132:133] op_sel:[0,1] op_sel_hi:[1,0]
	v_lshlrev_b32_e32 v132, 16, v17
	v_and_b32_e32 v133, 0xffff0000, v17
	v_and_b32_e32 v137, 0xffff0000, v16
	v_pk_fma_f32 v[132:133], v[24:25], v[8:9], v[132:133] op_sel_hi:[1,0,1] neg_lo:[1,0,0] neg_hi:[1,0,0]
	v_pk_fma_f32 v[16:17], v[22:23], v[8:9], v[136:137] op_sel_hi:[1,0,1] neg_lo:[1,0,0] neg_hi:[1,0,0]
	v_mov_b32_e32 v139, v133
	v_mov_b32_e32 v138, v17
	v_mov_b32_e32 v136, v16
; DI unsigned pk_bf16(float a, float b) { f32x2 v = {a, b}; return __builtin_bit_cast(unsigned, __builtin_convertvector(v, bf16v2)); }
; DI float xhalf_sum(float x) { auto rr = __builtin_amdgcn_permlane32_swap(__float_as_uint(x), __float_as_uint(x), false, false); return __uint_as_float(rr[0]) + __uint_as_float(rr[1]); }
;     ...
;             ss = xhalf_sum(ss);
;             const float rstd = rsqrtf(ss * (1.f / 128.f) + NORM_EPS) * 0.8f;
;             const float* sub = p.in[7];
; #pragma unroll
;             for (int dt = 0; dt < 4; ++dt)
; #pragma unroll
;                 for (int g4 = 0; g4 < 4; ++g4) {
;                     const int d = dt * 32 + 8 * g4 + 4 * h;
;                     const f32x4 sg = *(const f32x4*)(sub + d);
;                     u32x2 ov; ov.x = pk_bf16(o[dt][4 * g4] * rstd * sg[0], o[dt][4 * g4 + 1] * rstd * sg[1]);
;                     ov.y = pk_bf16(o[dt][4 * g4 + 2] * rstd * sg[2], o[dt][4 * g4 + 3] * rstd * sg[3]);
;                     *(u32x2*)(O + d) = ov;
;                 }
	v_mov_b32_e32 v137, v132
	v_pk_mul_f32 v[138:139], v[138:139], v[138:139]
	v_and_b32_e32 v143, 0xffff0000, v12
	v_pk_fma_f32 v[136:137], v[136:137], v[136:137], v[138:139]
	v_lshlrev_b32_e32 v138, 16, v13
	v_and_b32_e32 v139, 0xffff0000, v13
	v_pk_fma_f32 v[138:139], v[28:29], v[8:9], v[138:139] op_sel_hi:[1,0,1] neg_lo:[1,0,0] neg_hi:[1,0,0]
	v_pk_fma_f32 v[12:13], v[26:27], v[8:9], v[142:143] op_sel_hi:[1,0,1] neg_lo:[1,0,0] neg_hi:[1,0,0]
	v_mul_f32_e32 v140, v139, v139
	v_mul_f32_e32 v142, v13, v13
	v_pk_fma_f32 v[144:145], v[32:33], v[8:9], v[144:145] op_sel_hi:[1,0,1] neg_lo:[1,0,0] neg_hi:[1,0,0]
	v_pk_fma_f32 v[8:9], v[30:31], v[8:9], v[148:149] op_sel_hi:[1,0,1] neg_lo:[1,0,0] neg_hi:[1,0,0]
	v_pk_add_f32 v[136:137], v[136:137], v[136:137] op_sel:[0,1] op_sel_hi:[1,0]
	v_pk_fma_f32 v[140:141], v[138:139], v[138:139], v[140:141] op_sel_hi:[1,1,0]
	v_pk_fma_f32 v[142:143], v[12:13], v[12:13], v[142:143] op_sel_hi:[1,1,0]
	v_pk_mul_f32 v[146:147], v[144:145], v[144:145]
	v_pk_mul_f32 v[10:11], v[8:9], v[8:9]
	v_mov_b32_e32 v143, v146
	v_mov_b32_e32 v141, v147
	v_mov_b32_e32 v135, v10
	v_mov_b32_e32 v137, v11
	v_pk_add_f32 v[140:141], v[142:143], v[140:141]
	v_pk_add_f32 v[10:11], v[134:135], v[136:137]
	s_nop 0
	v_pk_add_f32 v[10:11], v[10:11], v[140:141]
	s_nop 0
	v_pk_add_f32 v[10:11], v[10:11], v[10:11] op_sel:[0,1] op_sel_hi:[1,0]
	s_nop 0
	v_mov_b32_e32 v11, v10
	s_nop 1
	v_permlane32_swap_b32_e32 v10, v11
	v_add_f32_e32 v10, v10, v11
	v_fmamk_f32 v10, v10, 0x3c000000, v181
	v_mul_f32_e32 v11, 0x4b800000, v10
	v_cmp_gt_f32_e32 vcc, s28, v10
	s_nop 1
	v_cndmask_b32_e32 v10, v10, v11, vcc
	v_rsq_f32_e32 v10, v10
	s_nop 0
	v_mul_f32_e32 v11, 0x45800000, v10
	v_cndmask_b32_e32 v10, v10, v11, vcc
	v_mul_f32_e32 v10, 0x3f4ccccd, v10
	v_pk_mul_f32 v[112:113], v[112:113], v[10:11] op_sel_hi:[1,0]
	v_pk_mul_f32 v[108:109], v[108:109], v[10:11] op_sel_hi:[1,0]
	s_waitcnt vmcnt(0)
	global_load_dwordx4 v[232:235], v[178:179], off offset:32
	global_load_dwordx4 v[150:153], v[178:179], off offset:64
	global_load_dwordx4 v[154:157], v[178:179], off offset:96
	v_pk_mul_f32 v[4:5], v[4:5], v[112:113]
	v_pk_mul_f32 v[6:7], v[6:7], v[108:109]
	v_cvt_pk_bf16_f32 v200, v4, v5
	v_cvt_pk_bf16_f32 v201, v6, v7
	global_load_dwordx4 v[4:7], v[178:179], off offset:128
	v_pk_mul_f32 v[106:107], v[106:107], v[10:11] op_sel_hi:[1,0]
	v_pk_mul_f32 v[102:103], v[102:103], v[10:11] op_sel_hi:[1,0]
	v_pk_mul_f32 v[96:97], v[96:97], v[10:11] op_sel_hi:[1,0]
	v_pk_mul_f32 v[92:93], v[92:93], v[10:11] op_sel_hi:[1,0]
	v_pk_mul_f32 v[90:91], v[90:91], v[10:11] op_sel_hi:[1,0]
	v_pk_mul_f32 v[86:87], v[86:87], v[10:11] op_sel_hi:[1,0]
	v_pk_mul_f32 v[84:85], v[84:85], v[10:11] op_sel_hi:[1,0]
	v_pk_mul_f32 v[82:83], v[82:83], v[10:11] op_sel_hi:[1,0]
	v_pk_mul_f32 v[14:15], v[14:15], v[10:11] op_sel_hi:[1,0]
	v_pk_mul_f32 v[12:13], v[12:13], v[10:11] op_sel_hi:[1,0]
	v_pk_mul_f32 v[8:9], v[8:9], v[10:11] op_sel_hi:[1,0]
	s_waitcnt vmcnt(3)
	v_pk_mul_f32 v[232:233], v[232:233], v[106:107]
	v_pk_mul_f32 v[234:235], v[234:235], v[102:103]
	v_cvt_pk_bf16_f32 v202, v232, v233
	v_cvt_pk_bf16_f32 v203, v234, v235
	global_load_dwordx4 v[232:235], v[178:179], off offset:160
	s_waitcnt vmcnt(3)
	v_pk_mul_f32 v[150:151], v[150:151], v[96:97]
	v_pk_mul_f32 v[152:153], v[152:153], v[92:93]
	v_cvt_pk_bf16_f32 v204, v150, v151
	v_cvt_pk_bf16_f32 v205, v152, v153
	global_load_dwordx4 v[150:153], v[178:179], off offset:192
	s_waitcnt vmcnt(3)
	v_pk_mul_f32 v[154:155], v[154:155], v[90:91]
	v_pk_mul_f32 v[156:157], v[156:157], v[86:87]
	v_cvt_pk_bf16_f32 v206, v154, v155
	v_cvt_pk_bf16_f32 v207, v156, v157
	global_load_dwordx4 v[154:157], v[178:179], off offset:224
	s_waitcnt vmcnt(3)
	v_pk_mul_f32 v[4:5], v[4:5], v[84:85]
	v_pk_mul_f32 v[6:7], v[6:7], v[82:83]
	v_cvt_pk_bf16_f32 v208, v4, v5
	v_cvt_pk_bf16_f32 v209, v6, v7
	global_load_dwordx4 v[4:7], v[178:179], off offset:256
	v_pk_mul_f32 v[82:83], v[100:101], v[10:11] op_sel_hi:[1,0]
	s_waitcnt vmcnt(3)
	v_pk_mul_f32 v[234:235], v[14:15], v[234:235]
	v_pk_mul_f32 v[232:233], v[82:83], v[232:233]
	v_pk_mul_f32 v[14:15], v[104:105], v[10:11] op_sel_hi:[1,0]
	v_cvt_pk_bf16_f32 v210, v232, v233
	v_cvt_pk_bf16_f32 v211, v234, v235
	global_load_dwordx4 v[232:235], v[178:179], off offset:288
	v_pk_mul_f32 v[82:83], v[94:95], v[10:11] op_sel_hi:[1,0]
	s_waitcnt vmcnt(3)
; DI unsigned pk_bf16(float a, float b) { f32x2 v = {a, b}; return __builtin_bit_cast(unsigned, __builtin_convertvector(v, bf16v2)); }
;     ...
; #pragma unroll
;             for (int dt = 0; dt < 4; ++dt)
; #pragma unroll
;                 for (int g4 = 0; g4 < 4; ++g4) {
;                     const int d = dt * 32 + 8 * g4 + 4 * h;
;                     const f32x4 sg = *(const f32x4*)(sub + d);
;                     u32x2 ov; ov.x = pk_bf16(o[dt][4 * g4] * rstd * sg[0], o[dt][4 * g4 + 1] * rstd * sg[1]);
;                     ov.y = pk_bf16(o[dt][4 * g4 + 2] * rstd * sg[2], o[dt][4 * g4 + 3] * rstd * sg[3]);
;                     *(u32x2*)(O + d) = ov;
;                 }
	v_pk_mul_f32 v[150:151], v[14:15], v[150:151]
	v_pk_mul_f32 v[152:153], v[82:83], v[152:153]
	v_cvt_pk_bf16_f32 v212, v150, v151
	v_cvt_pk_bf16_f32 v213, v152, v153
	global_load_dwordx4 v[150:153], v[178:179], off offset:320
	v_pk_mul_f32 v[14:15], v[116:117], v[10:11] op_sel_hi:[1,0]
	v_pk_mul_f32 v[82:83], v[110:111], v[10:11] op_sel_hi:[1,0]
	s_waitcnt vmcnt(3)
	v_pk_mul_f32 v[154:155], v[14:15], v[154:155]
	v_pk_mul_f32 v[156:157], v[82:83], v[156:157]
	v_cvt_pk_bf16_f32 v214, v154, v155
	v_cvt_pk_bf16_f32 v215, v156, v157
	global_load_dwordx4 v[154:157], v[178:179], off offset:352
	v_pk_mul_f32 v[14:15], v[122:123], v[10:11] op_sel_hi:[1,0]
	v_pk_mul_f32 v[82:83], v[114:115], v[10:11] op_sel_hi:[1,0]
	s_waitcnt vmcnt(3)
	v_pk_mul_f32 v[4:5], v[14:15], v[4:5]
	v_pk_mul_f32 v[6:7], v[82:83], v[6:7]
	v_cvt_pk_bf16_f32 v216, v4, v5
	v_cvt_pk_bf16_f32 v217, v6, v7
	global_load_dwordx4 v[4:7], v[178:179], off offset:384
	v_pk_mul_f32 v[14:15], v[124:125], v[10:11] op_sel_hi:[1,0]
	v_pk_mul_f32 v[82:83], v[118:119], v[10:11] op_sel_hi:[1,0]
	s_waitcnt vmcnt(3)
	v_pk_mul_f32 v[232:233], v[14:15], v[232:233]
	v_pk_mul_f32 v[234:235], v[82:83], v[234:235]
	v_cvt_pk_bf16_f32 v218, v232, v233
	v_cvt_pk_bf16_f32 v219, v234, v235
	global_load_dwordx4 v[232:235], v[178:179], off offset:416
	v_pk_mul_f32 v[14:15], v[128:129], v[10:11] op_sel_hi:[1,0]
	v_pk_mul_f32 v[82:83], v[126:127], v[10:11] op_sel_hi:[1,0]
	s_waitcnt vmcnt(3)
	v_pk_mul_f32 v[150:151], v[14:15], v[150:151]
	v_pk_mul_f32 v[152:153], v[82:83], v[152:153]
	v_cvt_pk_bf16_f32 v220, v150, v151
	v_cvt_pk_bf16_f32 v221, v152, v153
	global_load_dwordx4 v[150:153], v[178:179], off offset:448
	v_pk_mul_f32 v[14:15], v[130:131], v[10:11] op_sel_hi:[1,0]
	v_pk_mul_f32 v[82:83], v[120:121], v[10:11] op_sel_hi:[1,0]
	s_waitcnt vmcnt(3)
	v_pk_mul_f32 v[154:155], v[14:15], v[154:155]
	v_pk_mul_f32 v[156:157], v[82:83], v[156:157]
	v_cvt_pk_bf16_f32 v222, v154, v155
	v_cvt_pk_bf16_f32 v223, v156, v157
	global_load_dwordx4 v[154:157], v[178:179], off offset:480
	v_pk_mul_f32 v[14:15], v[88:89], v[10:11] op_sel_hi:[1,0]
	v_pk_mul_f32 v[82:83], v[98:99], v[10:11] op_sel_hi:[1,0]
	s_waitcnt vmcnt(3)
	v_pk_mul_f32 v[4:5], v[14:15], v[4:5]
	v_pk_mul_f32 v[6:7], v[82:83], v[6:7]
	v_cvt_pk_bf16_f32 v224, v4, v5
	v_cvt_pk_bf16_f32 v225, v6, v7
	v_pk_mul_f32 v[14:15], v[16:17], v[10:11] op_sel_hi:[1,0]
	v_pk_mul_f32 v[16:17], v[132:133], v[10:11] op_sel_hi:[1,0]
	s_waitcnt vmcnt(2)
	v_pk_mul_f32 v[232:233], v[14:15], v[232:233]
	v_pk_mul_f32 v[234:235], v[16:17], v[234:235]
	v_cvt_pk_bf16_f32 v226, v232, v233
	v_cvt_pk_bf16_f32 v227, v234, v235
	v_pk_mul_f32 v[14:15], v[138:139], v[10:11] op_sel_hi:[1,0]
	v_pk_mul_f32 v[10:11], v[144:145], v[10:11] op_sel_hi:[1,0]
	s_waitcnt vmcnt(1)
	v_pk_mul_f32 v[150:151], v[12:13], v[150:151]
	v_pk_mul_f32 v[152:153], v[14:15], v[152:153]
	v_cvt_pk_bf16_f32 v228, v150, v151
	v_cvt_pk_bf16_f32 v229, v152, v153
	s_waitcnt vmcnt(0)
	v_pk_mul_f32 v[154:155], v[8:9], v[154:155]
	v_pk_mul_f32 v[156:157], v[10:11], v[156:157]
	v_cvt_pk_bf16_f32 v230, v154, v155
	v_cvt_pk_bf16_f32 v231, v156, v157
	global_store_dwordx2 v[176:177], v[200:201], off
	global_store_dwordx2 v[176:177], v[202:203], off offset:16
	global_store_dwordx2 v[176:177], v[204:205], off offset:32
	global_store_dwordx2 v[176:177], v[206:207], off offset:48
	global_store_dwordx2 v[176:177], v[208:209], off offset:64
	global_store_dwordx2 v[176:177], v[210:211], off offset:80
	global_store_dwordx2 v[176:177], v[212:213], off offset:96
	global_store_dwordx2 v[176:177], v[214:215], off offset:112
	global_store_dwordx2 v[176:177], v[216:217], off offset:128
	global_store_dwordx2 v[176:177], v[218:219], off offset:144
	global_store_dwordx2 v[176:177], v[220:221], off offset:160
	global_store_dwordx2 v[176:177], v[222:223], off offset:176
	global_store_dwordx2 v[176:177], v[224:225], off offset:192
	global_store_dwordx2 v[176:177], v[226:227], off offset:208
	global_store_dwordx2 v[176:177], v[228:229], off offset:224
	global_store_dwordx2 v[176:177], v[230:231], off offset:240
	s_cbranch_execnz .LBB0_466
	s_branch .LBB0_482

;     ...
;     const u64 mysel = SEL[32 * hq + r];
;     const u64 U = ((UN[0] | UN[1]) | (UN[2] | UN[3])) | ((UN[4] | UN[5]) | (UN[6] | UN[7]));
;     {
;         const bf16_t* Ks = (const bf16_t*)(p.ws + OFF_KS) + (size_t)bg * 4096 * 64;
;         const bf16_t* VsT = (const bf16_t*)(p.ws + OFF_VST) + (size_t)bg * 64 * 4096;
;         const int nts = __popcll(U), j0 = __ffsll((long long)U) - 1;
;         f32x16 o[2];
; #pragma unroll
;         for (int dt = 0; dt < 2; ++dt)
; #pragma unroll
;             for (int i = 0; i < 16; ++i) o[dt][i] = 0.f;
;         float m = -1e30f; f32x16 lv;
; #pragma unroll
;         for (int i = 0; i < 16; ++i) lv[i] = 0.f;
;         kv_loop<64, true>(lds, Ks, VsT, 4096, nts, j0, [U](int j) { return __ffsll((long long)(U & (~0ull << (j + 1)))) - 1; }, [&](int j, const unsigned char* sb) {
.LBB0_538:
	s_or_b64 exec, exec, s[4:5]
	v_readlane_b32 s3, v238, 55
	s_add_i32 s2, 0, 0x19200
	s_waitcnt lgkmcnt(0)
	v_mov_b32_e32 v34, s3
	s_barrier
	ds_read_b128 v[34:37], v34
	v_mov_b32_e32 v38, s2
	ds_read_b128 v[38:41], v38
	v_readlane_b32 s2, v238, 56
	v_readlane_b32 s6, v238, 57
	s_waitcnt lgkmcnt(1)
	v_readfirstlane_b32 s3, v35
	v_mov_b32_e32 v42, s2
	ds_read_b128 v[42:45], v42
	v_readfirstlane_b32 s2, v34
	v_mov_b32_e32 v34, s6
	v_readfirstlane_b32 s5, v37
	v_readfirstlane_b32 s4, v36
	ds_read_b128 v[34:37], v34
	s_waitcnt lgkmcnt(2)
	v_readfirstlane_b32 s15, v39
	v_readfirstlane_b32 s14, v38
	v_readfirstlane_b32 s17, v41
	v_readfirstlane_b32 s16, v40
	s_or_b64 s[14:15], s[16:17], s[14:15]
	s_or_b64 s[2:3], s[14:15], s[2:3]
	s_waitcnt lgkmcnt(1)
	v_readfirstlane_b32 s7, v43
	v_readfirstlane_b32 s6, v42
	s_or_b64 s[2:3], s[2:3], s[4:5]
	v_readfirstlane_b32 s9, v45
	v_readfirstlane_b32 s8, v44
	s_or_b64 s[2:3], s[2:3], s[6:7]
	s_waitcnt lgkmcnt(0)
	v_readfirstlane_b32 s11, v35
	v_readfirstlane_b32 s10, v34
	s_or_b64 s[2:3], s[2:3], s[8:9]
	v_readfirstlane_b32 s13, v37
	v_readfirstlane_b32 s12, v36
	s_or_b64 s[2:3], s[2:3], s[10:11]
	v_lshlrev_b32_e32 v34, 3, v81
	v_lshlrev_b32_e32 v35, 3, v80
	s_or_b64 s[6:7], s[2:3], s[12:13]
	v_readlane_b32 s2, v238, 53
	v_add3_u32 v34, s75, v34, v35
	v_lshlrev_b32_e32 v36, 19, v122
	v_mov_b32_e32 v37, v173
	v_readlane_b32 s3, v238, 54
	s_cmp_eq_u64 s[6:7], 0
	ds_read_b64 v[124:125], v34
	v_lshl_add_u64 v[34:35], s[2:3], 0, v[36:37]
	s_cselect_b64 s[2:3], -1, 0
	s_ff1_i32_b64 s12, s[6:7]
	s_and_b64 vcc, s[2:3], exec
	s_cselect_b32 s2, -1, s12
	v_lshl_add_u32 v38, s2, 6, v187
	v_readlane_b32 s4, v238, 51
	v_ashrrev_i32_e32 v39, 31, v38
	v_readlane_b32 s5, v238, 52
	v_lshlrev_b64 v[38:39], 7, v[38:39]
	s_ashr_i32 s3, s2, 31
	v_lshl_add_u64 v[36:37], s[4:5], 0, v[36:37]
	v_lshl_add_u64 v[38:39], v[34:35], 0, v[38:39]
	s_lshl_b64 s[2:3], s[2:3], 13
	v_lshl_add_u64 v[38:39], v[38:39], 0, v[172:173]
	v_lshl_add_u64 v[40:41], v[36:37], 0, s[2:3]
	v_mov_b32_e32 v175, v173
	v_lshl_add_u64 v[40:41], v[40:41], 0, v[174:175]
	global_load_dwordx4 v[114:117], v[38:39], off
	global_load_dwordx4 v[118:121], v[40:41], off
	s_waitcnt vmcnt(1)
	ds_write_b128 v198, v[114:117]
	s_waitcnt vmcnt(0)
	ds_write2_b64 v199, v[118:119], v[120:121] offset0:128 offset1:130
	s_waitcnt lgkmcnt(0)
	s_barrier
	s_cbranch_vccnz .LBB0_556
	v_lshl_add_u64 v[126:127], v[34:35], 0, v[172:173]
	v_and_b32_e32 v34, 0xffffffc0, v203
	v_mov_b32_e32 v48, v173
	v_mov_b32_e32 v49, v173
	v_lshl_add_u64 v[128:129], v[36:37], 0, v[174:175]
	v_sub_u32_e32 v206, v178, v34
	v_mov_b32_e32 v34, v173
	v_mov_b32_e32 v35, v173
	v_mov_b32_e32 v36, v173
	v_mov_b32_e32 v37, v173
	v_mov_b32_e32 v38, v173
	v_mov_b32_e32 v39, v173
	v_mov_b32_e32 v40, v173
	v_mov_b32_e32 v41, v173
	v_mov_b32_e32 v42, v173
	v_mov_b32_e32 v43, v173
	v_mov_b32_e32 v44, v173
	v_mov_b32_e32 v45, v173
	v_mov_b32_e32 v46, v173
	v_mov_b32_e32 v47, v173
	v_mov_b64_e32 v[64:65], v[48:49]
	v_mov_b64_e32 v[80:81], v[48:49]
	s_bcnt1_i32_b64 s2, s[6:7]
	v_ashrrev_i32_e32 v131, 6, v203
	v_or_b32_e32 v132, 32, v181
	v_or_b32_e32 v133, 33, v181
	v_or_b32_e32 v134, 2, v181
	v_or_b32_e32 v135, 34, v181
	v_or_b32_e32 v136, 3, v181
	v_or_b32_e32 v137, 35, v181
	v_or_b32_e32 v138, 8, v181
	v_or_b32_e32 v139, 40, v181
	v_or_b32_e32 v140, 9, v181
	v_or_b32_e32 v141, 41, v181
	v_or_b32_e32 v142, 10, v181
	v_or_b32_e32 v143, 42, v181
	v_or_b32_e32 v144, 11, v181
	v_or_b32_e32 v145, 43, v181
	v_or_b32_e32 v162, 16, v181
	v_or_b32_e32 v163, 48, v181
	v_or_b32_e32 v164, 17, v181
	v_or_b32_e32 v165, 49, v181
	v_or_b32_e32 v166, 18, v181
	v_or_b32_e32 v167, 50, v181
	v_or_b32_e32 v168, 19, v181
	v_or_b32_e32 v169, 51, v181
	v_or_b32_e32 v175, 24, v181
	v_or_b32_e32 v186, 56, v181
	v_or_b32_e32 v188, 25, v181
	v_or_b32_e32 v189, 57, v181
	v_or_b32_e32 v190, 26, v181
	v_or_b32_e32 v191, 58, v181
	v_or_b32_e32 v192, 27, v181
	v_or_b32_e32 v193, 59, v181
	s_mov_b32 s13, 0
	v_mov_b32_e32 v207, 0xf149f2ca
	v_mov_b64_e32 v[62:63], v[46:47]
	v_mov_b64_e32 v[60:61], v[44:45]
	v_mov_b64_e32 v[58:59], v[42:43]
	v_mov_b64_e32 v[56:57], v[40:41]
	v_mov_b64_e32 v[54:55], v[38:39]
	v_mov_b64_e32 v[52:53], v[36:37]
	v_mov_b64_e32 v[50:51], v[34:35]
	v_mov_b64_e32 v[78:79], v[46:47]
	v_mov_b64_e32 v[76:77], v[44:45]
	v_mov_b64_e32 v[74:75], v[42:43]
	v_mov_b64_e32 v[72:73], v[40:41]
	v_mov_b64_e32 v[70:71], v[38:39]
	v_mov_b64_e32 v[68:69], v[36:37]
	v_mov_b64_e32 v[66:67], v[34:35]
	global_load_dword v192, v[184:185], off offset:4
	v_readfirstlane_b32 s28, v0
	v_readfirstlane_b32 s21, v131
	s_bfe_u32 s28, s28, 0x10008
	s_mov_b32 s13, 0
	s_mov_b32 s18, 0
	s_movk_i32 s19, 0x4800
	s_mov_b32 s20, 0x9000
	s_mov_b32 s8, s12
	s_mov_b32 s9, s12
	s_mov_b32 s10, s12

;     ...
;             const bool mine = (mysel >> j) & 1ull;
	v_lshrrev_b64 v[168:169], s12, v[124:125]
	v_and_b32_e32 v168, 1, v168
	v_cmp_ne_u32_e64 s[14:15], 0, v168

;     ...
;     for (int i = 0; i < nt; ++i) {
;         const int j = jn;
;         const bool more = (i + 1 < nt);
;         if (more) { jn = next(j); if (probe != 1) kv_gload<DV, HAS_V>(st, Kb, VTb, ldv, jn * 64); }
	s_cmp_lt_u32 s2, 2
	s_cbranch_scc1 .Lns_p1

;     ...
;         kv_loop<64, true>(lds, Ks, VsT, 4096, nts, j0, [U](int j) { return __ffsll((long long)(U & (~0ull << (j + 1)))) - 1; }, [&](int j, const unsigned char* sb) {
	s_add_i32 s22, s12, 1
	s_lshl_b64 s[22:23], -1, s22
	s_and_b64 s[22:23], s[22:23], s[6:7]
	s_ff1_i32_b64 s8, s[22:23]

; template <int DV, bool HAS_V>
; DI void kv_gload(KVStage<DV>& st, const bf16_t* __restrict__ Kb, const bf16_t* __restrict__ VTb, int ldv, int key0) {
;     const int tid = threadIdx.x;
;     st.k[0] = *(const u32x4*)(Kb + (size_t)(key0 + (tid >> 3)) * 64 + (tid & 7) * 8);
;     if (HAS_V) {
; #pragma unroll
;         for (int i = 0; i < DV / 64; ++i) { const int c = tid + 512 * i; st.v[i] = *(const u32x4*)(VTb + (size_t)(key0 >> 6) * (DV * 64) + c * 8); }
;     }
; }
	s_lshl_b32 s24, s8, 6
	v_add_u32_e32 v188, s24, v187
	v_mov_b32_e32 v189, v173
	v_lshlrev_b64 v[188:189], 7, v[188:189]
	v_lshl_add_u64 v[188:189], v[126:127], 0, v[188:189]
	global_load_dwordx4 v[114:117], v[188:189], off
	s_lshl_b32 s24, s8, 13
	s_mov_b32 s25, 0
	v_lshl_add_u64 v[190:191], v[128:129], 0, s[24:25]
	global_load_dwordx4 v[118:121], v[190:191], off

